# S5 scan items remapped so each XCD scans the sequences whose in_proj output it wrote itself (same panel-to-XCD mapping as the GEMM phases)
# speedup vs baseline: 1.0074x; 1.0074x over previous
; __global__ void __launch_bounds__(512, 2) hybrid_fwd(Args a) {
;     ...
;             int tid2 = threadIdx.x; asm volatile("" : "+v"(tid2)); const int lane2 = tid2 & 63;
;             const int w = wave * gg + bb; const int NGW2 = gg * 8;
;             for (int rep = 0; rep < REP_SCAN; ++rep) {
;     ...
;             for (int it = w; it < NB * 32 + NDB * 32; it += NGW2) scan_item(wsp, outp, ll, it, lds + wave * SCAN_LDS_WAVE, lane2);
.LBB0_440:
	s_or_b64 exec, exec, s[0:1]
	s_xor_b64 s[0:1], s[52:53], -1
	v_writelane_b32 v255, s0, 41
	s_mov_b32 s14, s88
	s_mov_b64 s[86:87], s[74:75]
	v_writelane_b32 v255, s1, 42
	s_mov_b32 s15, s83
	s_mov_b32 s88, s13
	v_readlane_b32 s0, v255, 5
	s_waitcnt lgkmcnt(0)
	s_barrier
	s_mul_i32 s0, s14, s0
	s_add_i32 s18, s0, s15
	s_lshl_b32 s83, s14, 3
	s_add_u32 s90, s86, 0x33c00000
	v_mov_b32_e32 v0, v242
	s_addc_u32 s91, s87, 0
	s_ashr_i32 s89, s88, 31
	s_cmpk_gt_i32 s18, 0x5ff
	v_and_b32_e32 v234, 63, v0
	s_cbranch_scc1 .LBB0_513
	s_add_u32 s17, s86, 0x1b600000
	s_addc_u32 s16, s87, 0
	s_lshl_b32 s68, s88, 5
	s_add_u32 s92, s90, 0x8100
	s_addc_u32 s93, s91, 0
	s_add_u32 s94, s90, 0x48100
	s_addc_u32 s95, s91, 0
	s_add_u32 s96, s90, 0x88100
	s_addc_u32 s97, s91, 0
	s_add_u32 s52, s90, 0xc8100
	s_addc_u32 s53, s91, 0
	s_lshl_b32 s0, s88, 9
	s_ashr_i32 s1, s0, 31
	s_lshl_b64 s[0:1], s[0:1], 2
	s_add_u32 s0, s90, s0
	s_addc_u32 s1, s91, s1
	s_add_u32 s69, s0, 0x108100
	s_addc_u32 s79, s1, 0
	s_lshl_b64 s[84:85], s[88:89], 9
	s_add_u32 s19, s86, 0x1f70c000
	s_addc_u32 s20, s87, 0
	s_add_u32 s21, s86, 0x1f77c000
	s_addc_u32 s22, s87, 0
	s_mov_b32 s64, s18
	s_mov_b32 s65, s18
	s_cmpk_gt_i32 s18, 0x3ff
	s_cbranch_scc1 .Lscan_noremap
	s_and_b32 s64, s18, 7
	s_lshl_b32 s64, s64, 7
	s_lshr_b32 s65, s18, 8
	s_lshl_b32 s65, s65, 5
	s_or_b32 s64, s64, s65
	s_bfe_u32 s65, s18, 0x50003
	s_or_b32 s64, s64, s65
	s_mov_b32 s65, s64
.Lscan_noremap:
	s_branch .LBB0_444
